# attention: first P.V fragment batch read from LDS under the exp/rescale VALU work instead of right before its MFMAs
# baseline (speedup 1.0000x reference)
.LBB0_1070:
	s_nop 1
	ds_bpermute_b32 v80, v126, v137
	v_max_f32_e32 v81, v137, v137
	s_waitcnt lgkmcnt(0)
	v_max_f32_e32 v80, v80, v80
	v_max_f32_e32 v80, v81, v80
	ds_bpermute_b32 v81, v125, v80
	s_waitcnt lgkmcnt(0)
	v_add_u32_e32 v188, 0x8800, v134
	ds_read_b128 v[156:159], v188
	ds_read_b128 v[160:163], v188 offset:64
	v_add_u32_e32 v188, 0x9000, v134
	ds_read_b128 v[164:167], v188 offset:256
	ds_read_b128 v[168:171], v188 offset:320
	v_add_u32_e32 v188, 0x9800, v134
	ds_read_b128 v[172:175], v188 offset:512
	ds_read_b128 v[176:179], v188 offset:576
	v_add_u32_e32 v188, 0xa000, v134
	ds_read_b128 v[180:183], v188 offset:768
	ds_read_b128 v[184:187], v188 offset:832
	v_max3_f32 v88, v136, v80, v81
	v_sub_f32_e32 v80, v136, v88
	v_exp_f32_e32 v90, v80
	v_sub_f32_e32 v80, v120, v88
	v_exp_f32_e32 v80, v80
	v_sub_f32_e32 v82, v121, v88
	v_exp_f32_e32 v82, v82
	v_sub_f32_e32 v83, v112, v88
	v_exp_f32_e32 v83, v83
	v_sub_f32_e32 v84, v113, v88
	v_exp_f32_e32 v84, v84
	v_sub_f32_e32 v85, v108, v88
	v_fma_f32 v81, v135, v90, v80
	v_exp_f32_e32 v85, v85
	v_sub_f32_e32 v86, v109, v88
	v_add_f32_e32 v81, v82, v81
	v_exp_f32_e32 v86, v86
	v_sub_f32_e32 v87, v106, v88
	v_add_f32_e32 v81, v83, v81
	v_exp_f32_e32 v87, v87
	v_sub_f32_e32 v89, v107, v88
	v_add_f32_e32 v81, v84, v81
	v_exp_f32_e32 v89, v89
	v_add_f32_e32 v81, v85, v81
	v_add_f32_e32 v81, v86, v81
	v_add_f32_e32 v81, v87, v81
	v_add_f32_e32 v91, v89, v81
	v_cvt_pk_bf16_f32 v81, v83, v84
	v_sub_f32_e32 v84, v110, v88
	v_cvt_pk_bf16_f32 v83, v87, v89
	v_exp_f32_e32 v89, v84
	v_sub_f32_e32 v84, v111, v88
	v_exp_f32_e32 v92, v84
	v_sub_f32_e32 v84, v114, v88
	v_exp_f32_e32 v93, v84
	v_sub_f32_e32 v84, v115, v88
	v_exp_f32_e32 v94, v84
	v_sub_f32_e32 v84, v116, v88
	v_exp_f32_e32 v95, v84
	v_sub_f32_e32 v84, v117, v88
	v_exp_f32_e32 v106, v84
	v_sub_f32_e32 v84, v118, v88
	v_exp_f32_e32 v107, v84
	v_sub_f32_e32 v84, v119, v88
	v_exp_f32_e32 v135, v84
	v_cvt_pk_bf16_f32 v84, v89, v92
	v_add_f32_e32 v89, v89, v91
	v_add_f32_e32 v89, v92, v89
	v_add_f32_e32 v89, v93, v89
	v_add_f32_e32 v89, v94, v89
	v_add_f32_e32 v89, v95, v89
	v_cvt_pk_bf16_f32 v80, v80, v82
	v_cvt_pk_bf16_f32 v82, v85, v86
	v_cvt_pk_bf16_f32 v85, v93, v94
	v_add_f32_e32 v89, v106, v89
	v_cvt_pk_bf16_f32 v86, v95, v106
	v_cvt_pk_bf16_f32 v87, v107, v135
	v_pk_mul_f32 v[74:75], v[74:75], v[90:91] op_sel_hi:[1,0]
	v_pk_mul_f32 v[72:73], v[72:73], v[90:91] op_sel_hi:[1,0]
	v_pk_mul_f32 v[70:71], v[70:71], v[90:91] op_sel_hi:[1,0]
	v_pk_mul_f32 v[68:69], v[68:69], v[90:91] op_sel_hi:[1,0]
	v_pk_mul_f32 v[58:59], v[58:59], v[90:91] op_sel_hi:[1,0]
	v_pk_mul_f32 v[56:57], v[56:57], v[90:91] op_sel_hi:[1,0]
	v_pk_mul_f32 v[18:19], v[18:19], v[90:91] op_sel_hi:[1,0]
	v_pk_mul_f32 v[16:17], v[16:17], v[90:91] op_sel_hi:[1,0]
	v_pk_mul_f32 v[30:31], v[30:31], v[90:91] op_sel_hi:[1,0]
	v_pk_mul_f32 v[28:29], v[28:29], v[90:91] op_sel_hi:[1,0]
	v_pk_mul_f32 v[22:23], v[22:23], v[90:91] op_sel_hi:[1,0]
	v_pk_mul_f32 v[20:21], v[20:21], v[90:91] op_sel_hi:[1,0]
	v_pk_mul_f32 v[26:27], v[26:27], v[90:91] op_sel_hi:[1,0]
	v_pk_mul_f32 v[24:25], v[24:25], v[90:91] op_sel_hi:[1,0]
	v_pk_mul_f32 v[78:79], v[78:79], v[90:91] op_sel_hi:[1,0]
	v_pk_mul_f32 v[76:77], v[76:77], v[90:91] op_sel_hi:[1,0]
	v_add_f32_e32 v89, v107, v89
	s_waitcnt lgkmcnt(7)
	v_mfma_f32_16x16x32_bf16 v[72:75], v[156:159], v[80:83], v[72:75]
	s_waitcnt lgkmcnt(5)
	v_mfma_f32_16x16x32_bf16 v[68:71], v[164:167], v[80:83], v[68:71]
	s_waitcnt lgkmcnt(3)
	v_mfma_f32_16x16x32_bf16 v[56:59], v[172:175], v[80:83], v[56:59]
	s_waitcnt lgkmcnt(1)
	v_mfma_f32_16x16x32_bf16 v[16:19], v[180:183], v[80:83], v[16:19]
	v_mfma_f32_16x16x32_bf16 v[72:75], v[160:163], v[84:87], v[72:75]
	v_mfma_f32_16x16x32_bf16 v[68:71], v[168:171], v[84:87], v[68:71]
	v_mfma_f32_16x16x32_bf16 v[56:59], v[176:179], v[84:87], v[56:59]
	s_waitcnt lgkmcnt(0)
	v_mfma_f32_16x16x32_bf16 v[16:19], v[184:187], v[84:87], v[16:19]
	v_add_u32_e32 v94, 0xa800, v134
	ds_read_b128 v[90:93], v94 offset:1024
	ds_read_b128 v[106:109], v94 offset:1088
	v_add_u32_e32 v94, 0xb000, v134
	ds_read_b128 v[110:113], v94 offset:1280
	ds_read_b128 v[114:117], v94 offset:1344
	v_add_u32_e32 v94, 0xb800, v134
	ds_read_b128 v[118:121], v94 offset:1536
	ds_read_b128 v[136:139], v94 offset:1600
	v_add_u32_e32 v94, 0xc000, v134
	ds_read_b128 v[140:143], v94 offset:1792
	ds_read_b128 v[144:147], v94 offset:1856
	s_waitcnt lgkmcnt(7)
	v_mfma_f32_16x16x32_bf16 v[28:31], v[90:93], v[80:83], v[28:31]
	s_waitcnt lgkmcnt(5)
	v_mfma_f32_16x16x32_bf16 v[20:23], v[110:113], v[80:83], v[20:23]
	s_waitcnt lgkmcnt(3)
	v_mfma_f32_16x16x32_bf16 v[24:27], v[118:121], v[80:83], v[24:27]
	s_waitcnt lgkmcnt(1)
	v_mfma_f32_16x16x32_bf16 v[76:79], v[140:143], v[80:83], v[76:79]
	v_mfma_f32_16x16x32_bf16 v[28:31], v[106:109], v[84:87], v[28:31]
	v_mfma_f32_16x16x32_bf16 v[20:23], v[114:117], v[84:87], v[20:23]
	v_mfma_f32_16x16x32_bf16 v[24:27], v[136:139], v[84:87], v[24:27]
	s_waitcnt lgkmcnt(0)
	v_mfma_f32_16x16x32_bf16 v[76:79], v[144:147], v[84:87], v[76:79]
	v_add_f32_e32 v135, v135, v89
	s_andn2_b64 vcc, exec, s[76:77]
	s_add_i32 s39, s39, 1
	s_cbranch_vccz .LBB0_1072
	v_mov_b32_e32 v136, v88
	v_add_u32_e32 v131, s32, v131
	v_add_u32_e32 v132, s32, v132
	v_add_u32_e32 v148, s32, v148
	v_add_u32_e32 v133, s32, v133
	v_add_u32_e32 v134, s32, v134
	s_sub_i32 s32, 0, s32
	s_branch .LBB0_1056

.LBB0_1124:
	s_nop 1
	ds_bpermute_b32 v80, v126, v137
	v_max_f32_e32 v81, v137, v137
	s_waitcnt lgkmcnt(0)
	v_max_f32_e32 v80, v80, v80
	v_max_f32_e32 v80, v81, v80
	ds_bpermute_b32 v81, v125, v80
	s_waitcnt lgkmcnt(0)
	v_add_u32_e32 v188, 0x8800, v134
	ds_read_b128 v[156:159], v188
	ds_read_b128 v[160:163], v188 offset:64
	v_add_u32_e32 v188, 0x9000, v134
	ds_read_b128 v[164:167], v188 offset:256
	ds_read_b128 v[168:171], v188 offset:320
	v_add_u32_e32 v188, 0x9800, v134
	ds_read_b128 v[172:175], v188 offset:512
	ds_read_b128 v[176:179], v188 offset:576
	v_add_u32_e32 v188, 0xa000, v134
	ds_read_b128 v[180:183], v188 offset:768
	ds_read_b128 v[184:187], v188 offset:832
	v_max3_f32 v88, v136, v80, v81
	v_sub_f32_e32 v80, v136, v88
	v_exp_f32_e32 v90, v80
	v_sub_f32_e32 v80, v120, v88
	v_exp_f32_e32 v80, v80
	v_sub_f32_e32 v82, v121, v88
	v_exp_f32_e32 v82, v82
	v_sub_f32_e32 v83, v112, v88
	v_exp_f32_e32 v83, v83
	v_sub_f32_e32 v84, v113, v88
	v_exp_f32_e32 v84, v84
	v_sub_f32_e32 v85, v108, v88
	v_fma_f32 v81, v135, v90, v80
	v_exp_f32_e32 v85, v85
	v_sub_f32_e32 v86, v109, v88
	v_add_f32_e32 v81, v82, v81
	v_exp_f32_e32 v86, v86
	v_sub_f32_e32 v87, v106, v88
	v_add_f32_e32 v81, v83, v81
	v_exp_f32_e32 v87, v87
	v_sub_f32_e32 v89, v107, v88
	v_add_f32_e32 v81, v84, v81
	v_exp_f32_e32 v89, v89
	v_add_f32_e32 v81, v85, v81
	v_add_f32_e32 v81, v86, v81
	v_add_f32_e32 v81, v87, v81
	v_add_f32_e32 v91, v89, v81
	v_cvt_pk_bf16_f32 v81, v83, v84
	v_sub_f32_e32 v84, v110, v88
	v_cvt_pk_bf16_f32 v83, v87, v89
	v_exp_f32_e32 v89, v84
	v_sub_f32_e32 v84, v111, v88
	v_exp_f32_e32 v92, v84
	v_sub_f32_e32 v84, v114, v88
	v_exp_f32_e32 v93, v84
	v_sub_f32_e32 v84, v115, v88
	v_exp_f32_e32 v94, v84
	v_sub_f32_e32 v84, v116, v88
	v_exp_f32_e32 v95, v84
	v_sub_f32_e32 v84, v117, v88
	v_exp_f32_e32 v106, v84
	v_sub_f32_e32 v84, v118, v88
	v_exp_f32_e32 v107, v84
	v_sub_f32_e32 v84, v119, v88
	v_exp_f32_e32 v135, v84
	v_cvt_pk_bf16_f32 v84, v89, v92
	v_add_f32_e32 v89, v89, v91
	v_add_f32_e32 v89, v92, v89
	v_add_f32_e32 v89, v93, v89
	v_add_f32_e32 v89, v94, v89
	v_add_f32_e32 v89, v95, v89
	v_cvt_pk_bf16_f32 v80, v80, v82
	v_cvt_pk_bf16_f32 v82, v85, v86
	v_cvt_pk_bf16_f32 v85, v93, v94
	v_add_f32_e32 v89, v106, v89
	v_cvt_pk_bf16_f32 v86, v95, v106
	v_cvt_pk_bf16_f32 v87, v107, v135
	v_pk_mul_f32 v[74:75], v[74:75], v[90:91] op_sel_hi:[1,0]
	v_pk_mul_f32 v[72:73], v[72:73], v[90:91] op_sel_hi:[1,0]
	v_pk_mul_f32 v[70:71], v[70:71], v[90:91] op_sel_hi:[1,0]
	v_pk_mul_f32 v[68:69], v[68:69], v[90:91] op_sel_hi:[1,0]
	v_pk_mul_f32 v[58:59], v[58:59], v[90:91] op_sel_hi:[1,0]
	v_pk_mul_f32 v[56:57], v[56:57], v[90:91] op_sel_hi:[1,0]
	v_pk_mul_f32 v[18:19], v[18:19], v[90:91] op_sel_hi:[1,0]
	v_pk_mul_f32 v[16:17], v[16:17], v[90:91] op_sel_hi:[1,0]
	v_pk_mul_f32 v[30:31], v[30:31], v[90:91] op_sel_hi:[1,0]
	v_pk_mul_f32 v[28:29], v[28:29], v[90:91] op_sel_hi:[1,0]
	v_pk_mul_f32 v[22:23], v[22:23], v[90:91] op_sel_hi:[1,0]
	v_pk_mul_f32 v[20:21], v[20:21], v[90:91] op_sel_hi:[1,0]
	v_pk_mul_f32 v[26:27], v[26:27], v[90:91] op_sel_hi:[1,0]
	v_pk_mul_f32 v[24:25], v[24:25], v[90:91] op_sel_hi:[1,0]
	v_pk_mul_f32 v[78:79], v[78:79], v[90:91] op_sel_hi:[1,0]
	v_pk_mul_f32 v[76:77], v[76:77], v[90:91] op_sel_hi:[1,0]
	v_add_f32_e32 v89, v107, v89
	s_waitcnt lgkmcnt(7)
	v_mfma_f32_16x16x32_bf16 v[72:75], v[156:159], v[80:83], v[72:75]
	s_waitcnt lgkmcnt(5)
	v_mfma_f32_16x16x32_bf16 v[68:71], v[164:167], v[80:83], v[68:71]
	s_waitcnt lgkmcnt(3)
	v_mfma_f32_16x16x32_bf16 v[56:59], v[172:175], v[80:83], v[56:59]
	s_waitcnt lgkmcnt(1)
	v_mfma_f32_16x16x32_bf16 v[16:19], v[180:183], v[80:83], v[16:19]
	v_mfma_f32_16x16x32_bf16 v[72:75], v[160:163], v[84:87], v[72:75]
	v_mfma_f32_16x16x32_bf16 v[68:71], v[168:171], v[84:87], v[68:71]
	v_mfma_f32_16x16x32_bf16 v[56:59], v[176:179], v[84:87], v[56:59]
	s_waitcnt lgkmcnt(0)
	v_mfma_f32_16x16x32_bf16 v[16:19], v[184:187], v[84:87], v[16:19]
	v_add_u32_e32 v94, 0xa800, v134
	ds_read_b128 v[90:93], v94 offset:1024
	ds_read_b128 v[106:109], v94 offset:1088
	v_add_u32_e32 v94, 0xb000, v134
	ds_read_b128 v[110:113], v94 offset:1280
	ds_read_b128 v[114:117], v94 offset:1344
	v_add_u32_e32 v94, 0xb800, v134
	ds_read_b128 v[118:121], v94 offset:1536
	ds_read_b128 v[136:139], v94 offset:1600
	v_add_u32_e32 v94, 0xc000, v134
	ds_read_b128 v[140:143], v94 offset:1792
	ds_read_b128 v[144:147], v94 offset:1856
	s_waitcnt lgkmcnt(7)
	v_mfma_f32_16x16x32_bf16 v[28:31], v[90:93], v[80:83], v[28:31]
	s_waitcnt lgkmcnt(5)
	v_mfma_f32_16x16x32_bf16 v[20:23], v[110:113], v[80:83], v[20:23]
	s_waitcnt lgkmcnt(3)
	v_mfma_f32_16x16x32_bf16 v[24:27], v[118:121], v[80:83], v[24:27]
	s_waitcnt lgkmcnt(1)
	v_mfma_f32_16x16x32_bf16 v[76:79], v[140:143], v[80:83], v[76:79]
	v_mfma_f32_16x16x32_bf16 v[28:31], v[106:109], v[84:87], v[28:31]
	v_mfma_f32_16x16x32_bf16 v[20:23], v[114:117], v[84:87], v[20:23]
	v_mfma_f32_16x16x32_bf16 v[24:27], v[136:139], v[84:87], v[24:27]
	s_waitcnt lgkmcnt(0)
	v_mfma_f32_16x16x32_bf16 v[76:79], v[144:147], v[84:87], v[76:79]
	v_add_f32_e32 v135, v135, v89
	s_andn2_b64 vcc, exec, s[76:77]
	s_add_i32 s42, s42, 1
	s_cbranch_vccz .LBB0_1100
	v_mov_b32_e32 v136, v88
	v_add_u32_e32 v131, s32, v131
	v_add_u32_e32 v132, s32, v132
	v_add_u32_e32 v148, s32, v148
	v_add_u32_e32 v133, s32, v133
	v_add_u32_e32 v134, s32, v134
	s_sub_i32 s32, 0, s32
	s_branch .LBB0_1110
